# v42 + qk_prep lane exchanges via DPP (quad_perm / row_shl,row_shr bank-masked) instead of ds_bpermute
# speedup vs baseline: 1.0120x; 1.0023x over previous
.LBB0_649:
	s_or_b64 exec, exec, s[22:23]
	s_waitcnt vmcnt(4)
	v_lshlrev_b32_e32 v118, 16, v78
	v_and_b32_e32 v119, 0xffff0000, v78
	v_lshlrev_b32_e32 v116, 16, v82
	v_and_b32_e32 v117, 0xffff0000, v82
	v_pk_mul_f32 v[106:107], v[118:119], v[118:119]
	v_and_b32_e32 v126, 0xffff0000, v79
	v_lshlrev_b32_e32 v127, 16, v79
	s_waitcnt vmcnt(3)
	v_lshlrev_b32_e32 v120, 16, v86
	v_and_b32_e32 v121, 0xffff0000, v86
	v_pk_fma_f32 v[106:107], v[116:117], v[116:117], v[106:107]
	v_and_b32_e32 v124, 0xffff0000, v83
	v_lshlrev_b32_e32 v125, 16, v83
	v_pk_mul_f32 v[78:79], v[126:127], v[126:127]
	v_and_b32_e32 v108, 0xffff0000, v80
	v_lshlrev_b32_e32 v109, 16, v80
	v_pk_fma_f32 v[122:123], v[120:121], v[120:121], v[106:107]
	v_and_b32_e32 v128, 0xffff0000, v87
	v_lshlrev_b32_e32 v129, 16, v87
	v_pk_fma_f32 v[78:79], v[124:125], v[124:125], v[78:79]
	v_and_b32_e32 v106, 0xffff0000, v84
	v_lshlrev_b32_e32 v107, 16, v84
	v_pk_mul_f32 v[82:83], v[108:109], v[108:109]
	v_pk_fma_f32 v[78:79], v[128:129], v[128:129], v[78:79]
	v_and_b32_e32 v86, 0xffff0000, v88
	v_lshlrev_b32_e32 v87, 16, v88
	v_pk_fma_f32 v[82:83], v[106:107], v[106:107], v[82:83]
	v_add_f32_e32 v0, v122, v123
	v_pk_fma_f32 v[130:131], v[86:87], v[86:87], v[82:83]
	v_and_b32_e32 v82, 0xffff0000, v85
	v_lshlrev_b32_e32 v83, 16, v85
	v_and_b32_e32 v84, 0xffff0000, v81
	v_lshlrev_b32_e32 v85, 16, v81
	v_add_f32_e32 v0, v79, v0
	v_and_b32_e32 v80, 0xffff0000, v89
	v_lshlrev_b32_e32 v81, 16, v89
	v_pk_mul_f32 v[88:89], v[84:85], v[84:85]
	v_add_f32_e32 v0, v78, v0
	v_pk_fma_f32 v[88:89], v[82:83], v[82:83], v[88:89]
	v_add_f32_e32 v0, v131, v0
	v_pk_fma_f32 v[88:89], v[80:81], v[80:81], v[88:89]
	v_add_f32_e32 v0, v130, v0
	v_add_f32_e32 v0, v89, v0
	v_add_f32_e32 v0, v88, v0
	s_nop 1
	v_mov_b32_dpp v78, v0 quad_perm:[1,0,3,2] row_mask:0xf bank_mask:0xf
	s_waitcnt lgkmcnt(0)
	ds_read_b128 v[54:57], v112
	ds_read_b128 v[50:53], v112 offset:16
	ds_read_b128 v[74:77], v112 offset:128
	ds_read_b128 v[70:73], v112 offset:144
	s_mov_b32 s9, 0xd000000
	s_waitcnt lgkmcnt(3)
	v_mov_b32_e32 v79, v54
	v_add_f32_e32 v0, v0, v78
	s_nop 1
	v_mov_b32_dpp v78, v0 quad_perm:[2,3,0,1] row_mask:0xf bank_mask:0xf
	s_mov_b64 s[22:23], 0xd000100
	v_lshl_add_u64 v[104:105], v[98:99], 0, s[22:23]
	s_add_i32 s8, s8, s10
	s_add_u32 s12, s12, s14
	s_waitcnt lgkmcnt(0)
	v_add_f32_e32 v0, v0, v78
	s_nop 1
	v_mov_b32_dpp v78, v0 row_shl:4 row_mask:0xf bank_mask:0x5
	v_mov_b32_dpp v78, v0 row_shr:4 row_mask:0xf bank_mask:0xa
	s_addc_u32 s13, s13, s15
	v_lshl_add_u64 v[90:91], v[90:91], 0, s[16:17]
	v_lshl_add_u64 v[92:93], v[92:93], 0, s[18:19]
	v_lshl_add_u64 v[94:95], v[94:95], 0, s[20:21]
	s_waitcnt lgkmcnt(0)
	v_add_f32_e32 v0, v0, v78
	v_fmamk_f32 v0, v0, 0x3baaaaab, v213
	v_cmp_gt_f32_e32 vcc, s89, v0
	v_mul_f32_e32 v78, 0x4b800000, v0
	v_lshl_add_u64 v[96:97], v[96:97], 0, s[20:21]
	v_cndmask_b32_e32 v0, v0, v78, vcc
	v_rsq_f32_e32 v0, v0
	s_cmp_lt_i32 s8, 0x8000
	v_mul_f32_e32 v78, 0x45800000, v0
	v_cndmask_b32_e32 v0, v0, v78, vcc
	v_mul_f32_e32 v0, 0x3dd53b94, v0
	v_mul_f32_e32 v78, v0, v116
	v_mul_f32_e32 v116, v2, v78
	v_mul_f32_e32 v78, v0, v118
	v_mul_f32_e32 v118, v10, v78
	v_mul_f32_e32 v78, v0, v120
	v_mul_f32_e32 v89, v34, v78
	s_nop 1
	v_mov_b32_dpp v78, v89 row_shl:4 row_mask:0xf bank_mask:0x5
	v_mov_b32_dpp v78, v89 row_shr:4 row_mask:0xf bank_mask:0xa
	v_mul_f32_e32 v54, v0, v117
	v_mul_f32_e32 v117, v3, v54
	v_mul_f32_e32 v54, v0, v119
	v_mul_f32_e32 v119, v11, v54
	s_waitcnt lgkmcnt(0)
	v_cndmask_b32_e64 v88, v78, -v78, s[4:5]
	v_mov_b32_e32 v78, v74
	v_pk_mul_f32 v[88:89], v[78:79], v[88:89]
	v_mul_f32_e32 v54, v0, v121
	v_add_f32_e32 v120, v88, v89
	v_mul_f32_e32 v89, v35, v54
	s_nop 1
	v_mov_b32_dpp v54, v89 row_shl:4 row_mask:0xf bank_mask:0x5
	v_mov_b32_dpp v54, v89 row_shr:4 row_mask:0xf bank_mask:0xa
	s_waitcnt lgkmcnt(0)
	v_cndmask_b32_e64 v88, v54, -v54, s[4:5]
	v_mov_b32_e32 v54, v75
	v_pk_mul_f32 v[74:75], v[54:55], v[88:89]
	s_nop 0
	v_add_f32_e32 v121, v74, v75
	v_mul_f32_e32 v74, v0, v125
	v_mul_f32_e32 v122, v4, v74
	v_mul_f32_e32 v74, v0, v127
	v_mul_f32_e32 v123, v12, v74
	v_mul_f32_e32 v74, v0, v129
	v_mul_f32_e32 v89, v36, v74
	s_nop 1
	v_mov_b32_dpp v74, v89 row_shl:4 row_mask:0xf bank_mask:0x5
	v_mov_b32_dpp v74, v89 row_shr:4 row_mask:0xf bank_mask:0xa
	v_mov_b32_e32 v75, v56
	v_mul_f32_e32 v56, v0, v124
	v_mul_f32_e32 v124, v5, v56
	v_mul_f32_e32 v56, v0, v126
	s_waitcnt lgkmcnt(0)
	v_cndmask_b32_e64 v88, v74, -v74, s[4:5]
	v_mov_b32_e32 v74, v76
	v_pk_mul_f32 v[88:89], v[74:75], v[88:89]
	v_mul_f32_e32 v126, v13, v56
	v_mul_f32_e32 v56, v0, v128
	v_add_f32_e32 v125, v88, v89
	v_mul_f32_e32 v89, v37, v56
	s_nop 1
	v_mov_b32_dpp v56, v89 row_shl:4 row_mask:0xf bank_mask:0x5
	v_mov_b32_dpp v56, v89 row_shr:4 row_mask:0xf bank_mask:0xa
	s_waitcnt lgkmcnt(0)
	v_cndmask_b32_e64 v88, v56, -v56, s[4:5]
	v_mov_b32_e32 v56, v77
	v_pk_mul_f32 v[76:77], v[56:57], v[88:89]
	s_nop 0
	v_add_f32_e32 v127, v76, v77
	v_mul_f32_e32 v76, v0, v107
	v_mul_f32_e32 v107, v6, v76
	v_mul_f32_e32 v76, v0, v109
	v_mul_f32_e32 v109, v14, v76
	v_mul_f32_e32 v76, v0, v87
	v_mul_f32_e32 v89, v38, v76
	s_nop 1
	v_mov_b32_dpp v76, v89 row_shl:4 row_mask:0xf bank_mask:0x5
	v_mov_b32_dpp v76, v89 row_shr:4 row_mask:0xf bank_mask:0xa
	v_mov_b32_e32 v77, v50
	v_mul_f32_e32 v50, v0, v106
	s_waitcnt lgkmcnt(0)
	v_cndmask_b32_e64 v88, v76, -v76, s[4:5]
	v_mov_b32_e32 v76, v70
	v_pk_mul_f32 v[88:89], v[76:77], v[88:89]
	s_nop 0
	v_add_f32_e32 v88, v88, v89
	v_mul_f32_e32 v89, v7, v50
	v_mul_f32_e32 v50, v0, v108
	v_mul_f32_e32 v106, v15, v50
	v_mul_f32_e32 v50, v0, v86
	v_mul_f32_e32 v87, v39, v50
	s_nop 1
	v_mov_b32_dpp v50, v87 row_shl:4 row_mask:0xf bank_mask:0x5
	v_mov_b32_dpp v50, v87 row_shr:4 row_mask:0xf bank_mask:0xa
	s_waitcnt lgkmcnt(0)
	v_cndmask_b32_e64 v86, v50, -v50, s[4:5]
	v_mov_b32_e32 v50, v71
	v_pk_mul_f32 v[70:71], v[50:51], v[86:87]
	s_nop 0
	v_add_f32_e32 v108, v70, v71
	v_mul_f32_e32 v70, v0, v83
	v_mul_f32_e32 v83, v8, v70
	v_mul_f32_e32 v70, v0, v85
	v_mul_f32_e32 v85, v16, v70
	v_mul_f32_e32 v70, v0, v81
	v_mul_f32_e32 v87, v40, v70
	s_nop 1
	v_mov_b32_dpp v70, v87 row_shl:4 row_mask:0xf bank_mask:0x5
	v_mov_b32_dpp v70, v87 row_shr:4 row_mask:0xf bank_mask:0xa
	v_mov_b32_e32 v71, v52
	v_mul_f32_e32 v52, v0, v82
	s_waitcnt lgkmcnt(0)
	v_cndmask_b32_e64 v86, v70, -v70, s[4:5]
	v_mov_b32_e32 v70, v72
	v_pk_mul_f32 v[86:87], v[70:71], v[86:87]
	s_nop 0
	v_add_f32_e32 v86, v86, v87
	v_mul_f32_e32 v87, v9, v52
	v_mul_f32_e32 v52, v0, v84
	v_mul_f32_e32 v0, v0, v80
	v_mul_f32_e32 v81, v41, v0
	s_nop 1
	v_mov_b32_dpp v0, v81 row_shl:4 row_mask:0xf bank_mask:0x5
	v_mov_b32_dpp v0, v81 row_shr:4 row_mask:0xf bank_mask:0xa
	v_mul_f32_e32 v84, v17, v52
	v_mov_b32_e32 v52, v73
	s_waitcnt lgkmcnt(0)
	v_cndmask_b32_e64 v80, v0, -v0, s[4:5]
	v_pk_mul_f32 v[72:73], v[52:53], v[80:81]
	v_cvt_pk_bf16_f32 v80, v116, v117
	v_cvt_pk_bf16_f32 v81, v122, v124
	v_cvt_pk_bf16_f32 v82, v107, v89
	v_cvt_pk_bf16_f32 v83, v83, v87
	global_store_dwordx4 v[102:103], v[80:83], off
	v_add_f32_e32 v0, v72, v73
	v_add_co_u32_e32 v72, vcc, s9, v100
	v_cvt_pk_bf16_f32 v80, v118, v119
	v_cvt_pk_bf16_f32 v81, v123, v126
	v_cvt_pk_bf16_f32 v82, v109, v106
	v_cvt_pk_bf16_f32 v83, v85, v84
	s_nop 1
	v_addc_co_u32_e32 v73, vcc, 0, v101, vcc
	s_waitcnt vmcnt(3)
	v_lshlrev_b32_e32 v102, 16, v62
	v_and_b32_e32 v103, 0xffff0000, v62
	global_store_dwordx4 v[72:73], v[80:83], off offset:16
	s_waitcnt vmcnt(3)
	v_and_b32_e32 v89, 0xffff0000, v66
	v_pk_mul_f32 v[72:73], v[102:103], v[102:103]
	v_cvt_pk_bf16_f32 v80, v120, v121
	v_cvt_pk_bf16_f32 v81, v125, v127
	v_cvt_pk_bf16_f32 v82, v88, v108
	v_cvt_pk_bf16_f32 v83, v86, v0
	v_lshlrev_b32_e32 v88, 16, v66
	v_and_b32_e32 v86, 0xffff0000, v63
	v_lshlrev_b32_e32 v87, 16, v63
	global_store_dwordx4 v[104:105], v[80:83], off
	s_waitcnt vmcnt(3)
	v_lshlrev_b32_e32 v104, 16, v58
	v_and_b32_e32 v105, 0xffff0000, v58
	v_pk_fma_f32 v[72:73], v[88:89], v[88:89], v[72:73]
	v_and_b32_e32 v84, 0xffff0000, v67
	v_lshlrev_b32_e32 v85, 16, v67
	v_and_b32_e32 v82, 0xffff0000, v59
	v_lshlrev_b32_e32 v83, 16, v59
	v_pk_mul_f32 v[58:59], v[86:87], v[86:87]
	v_pk_fma_f32 v[106:107], v[104:105], v[104:105], v[72:73]
	v_pk_fma_f32 v[58:59], v[84:85], v[84:85], v[58:59]
	v_and_b32_e32 v80, 0xffff0000, v64
	v_lshlrev_b32_e32 v81, 16, v64
	v_pk_fma_f32 v[108:109], v[82:83], v[82:83], v[58:59]
	v_and_b32_e32 v72, 0xffff0000, v68
	v_lshlrev_b32_e32 v73, 16, v68
	v_pk_mul_f32 v[58:59], v[80:81], v[80:81]
	v_add_f32_e32 v0, v106, v107
	v_and_b32_e32 v66, 0xffff0000, v60
	v_lshlrev_b32_e32 v67, 16, v60
	v_pk_fma_f32 v[58:59], v[72:73], v[72:73], v[58:59]
	v_and_b32_e32 v64, 0xffff0000, v65
	v_lshlrev_b32_e32 v65, 16, v65
	v_add_f32_e32 v0, v109, v0
	v_pk_fma_f32 v[116:117], v[66:67], v[66:67], v[58:59]
	v_and_b32_e32 v62, 0xffff0000, v69
	v_lshlrev_b32_e32 v63, 16, v69
	v_and_b32_e32 v58, 0xffff0000, v61
	v_lshlrev_b32_e32 v59, 16, v61
	v_pk_mul_f32 v[60:61], v[64:65], v[64:65]
	v_add_f32_e32 v0, v108, v0
	v_pk_fma_f32 v[60:61], v[62:63], v[62:63], v[60:61]
	v_add_f32_e32 v0, v117, v0
	v_pk_fma_f32 v[60:61], v[58:59], v[58:59], v[60:61]
	v_add_f32_e32 v0, v116, v0
	v_add_f32_e32 v0, v61, v0
	v_add_f32_e32 v0, v60, v0
	s_nop 1
	v_mov_b32_dpp v60, v0 quad_perm:[1,0,3,2] row_mask:0xf bank_mask:0xf
	s_mov_b32 s9, 0x7000000
	s_waitcnt lgkmcnt(0)
	v_add_f32_e32 v0, v0, v60
	s_nop 1
	v_mov_b32_dpp v60, v0 quad_perm:[2,3,0,1] row_mask:0xf bank_mask:0xf
	s_waitcnt lgkmcnt(0)
	v_add_f32_e32 v0, v0, v60
	s_nop 1
	v_mov_b32_dpp v60, v0 row_shl:4 row_mask:0xf bank_mask:0x5
	v_mov_b32_dpp v60, v0 row_shr:4 row_mask:0xf bank_mask:0xa
	s_waitcnt lgkmcnt(0)
	v_add_f32_e32 v0, v0, v60
	v_fmamk_f32 v0, v0, 0x3baaaaab, v213
	v_cmp_gt_f32_e32 vcc, s89, v0
	v_mul_f32_e32 v60, 0x4b800000, v0
	s_nop 0
	v_cndmask_b32_e32 v0, v0, v60, vcc
	v_rsq_f32_e32 v0, v0
	s_nop 0
	v_mul_f32_e32 v60, 0x45800000, v0
	v_cndmask_b32_e32 v0, v0, v60, vcc
	v_mul_f32_e32 v60, v0, v88
	v_mul_f32_e32 v68, v18, v60
	v_mul_f32_e32 v60, v0, v102
	v_mul_f32_e32 v69, v26, v60
	v_mul_f32_e32 v60, v0, v104
	v_mul_f32_e32 v61, v42, v60
	s_nop 1
	v_mov_b32_dpp v60, v61 row_shl:4 row_mask:0xf bank_mask:0x5
	v_mov_b32_dpp v60, v61 row_shr:4 row_mask:0xf bank_mask:0xa
	s_waitcnt lgkmcnt(0)
	v_cndmask_b32_e64 v60, v60, -v60, s[4:5]
	v_pk_mul_f32 v[60:61], v[78:79], v[60:61]
	s_nop 0
	v_add_f32_e32 v78, v60, v61
	v_mul_f32_e32 v60, v0, v89
	v_mul_f32_e32 v79, v19, v60
	v_mul_f32_e32 v60, v0, v103
	v_mul_f32_e32 v88, v27, v60
	v_mul_f32_e32 v60, v0, v105
	v_mul_f32_e32 v61, v43, v60
	s_nop 1
	v_mov_b32_dpp v60, v61 row_shl:4 row_mask:0xf bank_mask:0x5
	v_mov_b32_dpp v60, v61 row_shr:4 row_mask:0xf bank_mask:0xa
	s_waitcnt lgkmcnt(0)
	v_cndmask_b32_e64 v60, v60, -v60, s[4:5]
	v_pk_mul_f32 v[54:55], v[54:55], v[60:61]
	s_nop 0
	v_add_f32_e32 v60, v54, v55
	v_mul_f32_e32 v54, v0, v85
	v_mul_f32_e32 v61, v20, v54
	v_mul_f32_e32 v54, v0, v87
	v_mul_f32_e32 v85, v28, v54
	v_mul_f32_e32 v54, v0, v83
	v_mul_f32_e32 v55, v44, v54
	s_nop 1
	v_mov_b32_dpp v54, v55 row_shl:4 row_mask:0xf bank_mask:0x5
	v_mov_b32_dpp v54, v55 row_shr:4 row_mask:0xf bank_mask:0xa
	s_waitcnt lgkmcnt(0)
	v_cndmask_b32_e64 v54, v54, -v54, s[4:5]
	v_pk_mul_f32 v[54:55], v[74:75], v[54:55]
	s_nop 0
	v_add_f32_e32 v74, v54, v55
	v_mul_f32_e32 v54, v0, v84
	v_mul_f32_e32 v75, v21, v54
	v_mul_f32_e32 v54, v0, v86
	v_mul_f32_e32 v83, v29, v54
	v_mul_f32_e32 v54, v0, v82
	v_mul_f32_e32 v55, v45, v54
	s_nop 1
	v_mov_b32_dpp v54, v55 row_shl:4 row_mask:0xf bank_mask:0x5
	v_mov_b32_dpp v54, v55 row_shr:4 row_mask:0xf bank_mask:0xa
	s_waitcnt lgkmcnt(0)
	v_cndmask_b32_e64 v54, v54, -v54, s[4:5]
	v_pk_mul_f32 v[54:55], v[56:57], v[54:55]
	s_nop 0
	v_add_f32_e32 v56, v54, v55
	v_mul_f32_e32 v54, v0, v73
	v_mul_f32_e32 v57, v22, v54
	v_mul_f32_e32 v54, v0, v81
	v_mul_f32_e32 v73, v30, v54
	v_mul_f32_e32 v54, v0, v67
	v_mul_f32_e32 v55, v46, v54
	s_nop 1
	v_mov_b32_dpp v54, v55 row_shl:4 row_mask:0xf bank_mask:0x5
	v_mov_b32_dpp v54, v55 row_shr:4 row_mask:0xf bank_mask:0xa
	s_waitcnt lgkmcnt(0)
	v_cndmask_b32_e64 v54, v54, -v54, s[4:5]
	v_pk_mul_f32 v[54:55], v[76:77], v[54:55]
	s_nop 0
	v_add_f32_e32 v67, v54, v55
	v_mul_f32_e32 v54, v0, v72
	v_mul_f32_e32 v72, v23, v54
	v_mul_f32_e32 v54, v0, v80
	v_mul_f32_e32 v76, v31, v54
	v_mul_f32_e32 v54, v0, v66
	v_mul_f32_e32 v55, v47, v54
	s_nop 1
	v_mov_b32_dpp v54, v55 row_shl:4 row_mask:0xf bank_mask:0x5
	v_mov_b32_dpp v54, v55 row_shr:4 row_mask:0xf bank_mask:0xa
	s_waitcnt lgkmcnt(0)
	v_cndmask_b32_e64 v54, v54, -v54, s[4:5]
	v_pk_mul_f32 v[50:51], v[50:51], v[54:55]
	s_nop 0
	v_add_f32_e32 v66, v50, v51
	v_mul_f32_e32 v50, v0, v63
	v_mul_f32_e32 v54, v24, v50
	v_mul_f32_e32 v50, v0, v65
	v_mul_f32_e32 v63, v32, v50
	v_mul_f32_e32 v50, v0, v59
	v_mul_f32_e32 v51, v48, v50
	s_nop 1
	v_mov_b32_dpp v50, v51 row_shl:4 row_mask:0xf bank_mask:0x5
	v_mov_b32_dpp v50, v51 row_shr:4 row_mask:0xf bank_mask:0xa
	s_waitcnt lgkmcnt(0)
	v_cndmask_b32_e64 v50, v50, -v50, s[4:5]
	v_pk_mul_f32 v[50:51], v[70:71], v[50:51]
	s_nop 0
	v_add_f32_e32 v59, v50, v51
	v_mul_f32_e32 v50, v0, v62
	v_mul_f32_e32 v55, v25, v50
	v_mul_f32_e32 v50, v0, v64
	v_mul_f32_e32 v0, v0, v58
	v_mul_f32_e32 v51, v49, v0
	s_nop 1
	v_mov_b32_dpp v0, v51 row_shl:4 row_mask:0xf bank_mask:0x5
	v_mov_b32_dpp v0, v51 row_shr:4 row_mask:0xf bank_mask:0xa
	v_mul_f32_e32 v62, v33, v50
	s_waitcnt lgkmcnt(0)
	v_cndmask_b32_e64 v50, v0, -v0, s[4:5]
	v_pk_mul_f32 v[50:51], v[52:53], v[50:51]
	s_nop 0
	v_add_f32_e32 v0, v50, v51
	v_cvt_pk_bf16_f32 v50, v68, v79
	v_cvt_pk_bf16_f32 v51, v61, v75
	v_cvt_pk_bf16_f32 v52, v57, v72
	v_cvt_pk_bf16_f32 v53, v54, v55
	v_add_co_u32_e32 v54, vcc, s9, v100
	s_nop 1
	v_addc_co_u32_e32 v55, vcc, 0, v101, vcc
	global_store_dwordx4 v[54:55], v[50:53], off
	s_nop 1
	v_cvt_pk_bf16_f32 v50, v69, v88
	v_cvt_pk_bf16_f32 v51, v85, v83
	v_cvt_pk_bf16_f32 v52, v73, v76
	v_cvt_pk_bf16_f32 v53, v63, v62
	global_store_dwordx4 v[54:55], v[50:53], off offset:16
	v_add_co_u32_e32 v54, vcc, s9, v98
	s_nop 0
	v_cvt_pk_bf16_f32 v50, v78, v60
	v_cvt_pk_bf16_f32 v51, v74, v56
	v_cvt_pk_bf16_f32 v52, v67, v66
	v_cvt_pk_bf16_f32 v53, v59, v0
	s_nop 0
	v_addc_co_u32_e32 v55, vcc, 0, v99, vcc
	global_store_dwordx4 v[54:55], v[50:53], off offset:256
	s_cbranch_scc0 .LBB0_652
